# up-GEMM K-loop LDS-DMA issue rebalanced 2/6/2/6 -> 4/4/4/4 per super-phase (Bs[b][1] pair staged one super-phase later), saddr-form DMA addresses
# baseline (speedup 1.0000x reference)
; __device__ __forceinline__ int otid() { int t = threadIdx.x; asm volatile("" : "+v"(t)); return t; }
; #define PG8_STAGE(bufoff, gbase, voff) do { _Pragma("unroll") for (int _i = 0; _i < 2; ++_i) \
;         __builtin_amdgcn_global_load_lds((const unsigned*)((const char*)(gbase) + (voff)[_i]), (PG8_LAS unsigned*)(lds + (bufoff) + ldsw + _i * 8192), 16, 0, 0); } while (0)
; #define PG8_WAIT_V(n) asm volatile("s_waitcnt vmcnt(" #n ")" ::: "memory")
; #define PG8_BAR __builtin_amdgcn_s_barrier()
; template <class Epi, class Sched, bool ALIGN_EPI = false, bool SP2 = false>
; __device__ __forceinline__ void gemm_phase(PG8_LAS unsigned char* lds, const Gemm g, const Sched& S, const Epi& E) {
;     const int tid = otid(), wid = __builtin_amdgcn_readfirstlane(tid >> 6), lane = tid & 63, wr = wid >> 2, wc = wid & 3, fr = lane & 15, fq = lane >> 4;
;     const int K = g.K, nt = K / BK;
;     unsigned voffA[2], voffB[2];
; #pragma unroll
;     for (int i = 0; i < 2; ++i) { int R, C; stage_rc(tid * 16 + i * 8192, R, C); const int Rb = Epi::PERM ? ((R & ~31) + perm32(R & 31)) : R;
;         voffA[i] = (unsigned)(R * g.lda + C) * 2u; voffB[i] = (unsigned)(Rb * K + C) * 2u; }
;     const size_t kstep = (size_t)(BK * 2);
;     const size_t hstepB = (size_t)HALF * K * 2, hstepA = (size_t)HALF * g.lda * 2;
;     const size_t tstepA = 2 * hstepA, tstepB = 2 * hstepB;
;     const unsigned ldsw = (unsigned)wid * 1024u;
;     const int aoff = lds_byte(wr * 64 + fr, fq * 8), boff = lds_byte(wc * 32 + fr, fq * 8);
;     ...
;         PG8_STAGE(PG8_SB(1, 0), cB + kstep, voffB); PG8_STAGE(PG8_SA(1, 0), cA + kstep, voffA); PG8_STAGE(PG8_SB(1, 1), cB + hstepB + kstep, voffB);
;         PG8_WAIT_V(6); PG8_BAR;
.LBB0_438:
	s_lshl_b32 s13, s13, 5
	s_and_b32 s21, s13, 0x60
	s_add_i32 m0, s19, 0x18000
	v_lshl_add_u64 v[6:7], v[6:7], 0, s[48:49]
	s_lshl_b32 s20, s12, 13
	s_lshl_b32 s13, s21, 7
	s_waitcnt vmcnt(2)
	s_barrier
	global_load_lds_dwordx4 v[6:7], off
	v_lshl_add_u64 v[4:5], v[4:5], 0, s[48:49]
	s_add_i32 m0, s19, 0x1a000
	s_add_i32 s70, s19, 0x8000
	s_add_i32 s71, s19, 0xa000
	global_load_lds_dwordx4 v[4:5], off
	v_lshl_add_u64 v[0:1], v[0:1], 0, s[48:49]
	s_mov_b32 m0, s70
	s_add_u32 s82, s64, 0x40080
	s_addc_u32 s83, s65, 0
	s_add_u32 s14, s64, 0x40080
	global_load_lds_dwordx4 v[0:1], off
	v_lshl_add_u64 v[0:1], v[2:3], 0, s[48:49]
	s_mov_b32 m0, s71
	s_addc_u32 s15, s65, 0
	global_load_lds_dwordx4 v[0:1], off
	s_add_i32 m0, s19, 0x1c000
	v_lshl_add_u64 v[0:1], s[14:15], 0, v[144:145]
	global_load_lds_dwordx4 v[0:1], off
	v_lshl_add_u64 v[0:1], s[14:15], 0, v[128:129]
	s_add_i32 m0, s19, 0x1e000
	s_cmpk_lt_u32 s9, 0x100
	global_load_lds_dwordx4 v[0:1], off
	v_lshrrev_b32_e32 v1, 1, v8
	v_and_b32_e32 v1, 24, v1
	v_and_b32_e32 v0, 15, v8
	v_lshlrev_b32_e32 v2, 1, v1
	v_lshl_or_b32 v142, s12, 6, v0
	v_lshl_or_b32 v0, v0, 6, v2
	v_lshlrev_b32_e32 v2, 2, v8
	v_and_b32_e32 v2, 32, v2
	v_bitop3_b32 v3, v0, s20, v2 bitop3:0xde
	v_bitop3_b32 v143, v0, s13, v2 bitop3:0xde
	v_lshlrev_b32_e32 v0, 14, v9
	v_and_b32_e32 v0, 0xffff8000, v0
	v_or_b32_e32 v146, s21, v1
	v_lshl_add_u32 v0, v10, 11, v0
	v_and_b32_e32 v1, 1, v9
	v_lshl_or_b32 v0, v1, 6, v0
	v_lshl_add_u32 v134, v11, 1, v0
	v_lshlrev_b32_e32 v0, 14, v13
	v_and_b32_e32 v0, 0xffff8000, v0
	s_waitcnt vmcnt(6)
	v_lshl_add_u32 v0, v12, 11, v0
	v_and_b32_e32 v1, 1, v13
	v_lshl_or_b32 v0, v1, 6, v0
	s_sext_i32_i16 s63, s8
	s_cselect_b64 s[12:13], -1, 0
	s_waitcnt lgkmcnt(0)
	s_ashr_i32 s72, s37, 31
	v_mov_b32_e32 v135, v145
	v_lshl_add_u32 v136, v14, 1, v0
	v_mov_b32_e32 v137, v145
	s_mov_b32 s73, 0
	v_add_u32_e32 v147, 0, v3
	s_barrier
	s_branch .LBB0_441

; #define PG8_STAGE(bufoff, gbase, voff) do { _Pragma("unroll") for (int _i = 0; _i < 2; ++_i) \
;         __builtin_amdgcn_global_load_lds((const unsigned*)((const char*)(gbase) + (voff)[_i]), (PG8_LAS unsigned*)(lds + (bufoff) + ldsw + _i * 8192), 16, 0, 0); } while (0)
; #define PG8_LDA(dst, b, h) do { _Pragma("unroll") for (int m = 0; m < 4; ++m) _Pragma("unroll") for (int k = 0; k < 2; ++k) dst[m][k] = *(const PG8_LAS bf16x8*)(lds + PG8_SA(b, h) + aoff + m * 2048 + k * 1024); } while (0)
; #define PG8_LDB(dst, b, h) do { _Pragma("unroll") for (int n = 0; n < 2; ++n) _Pragma("unroll") for (int k = 0; k < 2; ++k) dst[n][k] = *(const PG8_LAS bf16x8*)(lds + PG8_SB(b, h) + boff + n * 2048 + k * 1024); } while (0)
; #define PG8_WAIT_V(n) asm volatile("s_waitcnt vmcnt(" #n ")" ::: "memory")
; #define PG8_WAIT_L(n) asm volatile("s_waitcnt lgkmcnt(" #n ")" ::: "memory")
; #define PG8_BAR __builtin_amdgcn_s_barrier()
; #define PG8_SCHED __builtin_amdgcn_sched_barrier(0)
; template <class Epi, class Sched, bool ALIGN_EPI = false, bool SP2 = false>
; __device__ __forceinline__ void gemm_phase(PG8_LAS unsigned char* lds, const Gemm g, const Sched& S, const Epi& E) {
;     ...
;         const bool has_next = S.next(ui + 1, nxt);
;         const char* nA = has_next ? (const char*)g.A + (size_t)nxt.pm * tstepA : cA; const char* nB = has_next ? (const char*)g.Bt + (size_t)nxt.pn * tstepB : cB;
;         for (int t = 0; t < nt; t += 2) {
;             const bool last = (t == nt - 2);
;             const char* a1 = cA + (size_t)(t + 1) * kstep;
;             const char* a2 = last ? nA : cA + (size_t)(t + 2) * kstep; const char* b2 = last ? nB : cB + (size_t)(t + 2) * kstep;
;             const char* a3 = a2 + kstep; const char* b3 = b2 + kstep;
;             if (last && has_next) S.a_ready(nxt);
;             if constexpr (SP2) {
;             PG8_LDB(B0, 0, 0); PG8_LDB(B1, 0, 1); PG8_SCHED; PG8_LDA(At, 0, 0); PG8_STAGE(PG8_SA(1, 1), a1 + hstepA, voffA);
;             PG8_WAIT_V(8); PG8_WAIT_L(0); PG8_BAR; PG8_MMA(0, 0, At, B0); PG8_MMA(0, 1, At, B1); PG8_BAR; PG8_SCHED;
;             PG8_LDA(At, 0, 1); PG8_STAGE(PG8_SB(0, 0), b2, voffB); PG8_STAGE(PG8_SB(0, 1), b2 + hstepB, voffB); PG8_STAGE(PG8_SA(0, 0), a2, voffA);
;             PG8_WAIT_V(8); PG8_WAIT_L(0); PG8_BAR; PG8_MMA(1, 0, At, B0); PG8_MMA(1, 1, At, B1); PG8_BAR; PG8_SCHED;
.LBB0_443:
	s_ashr_i32 s21, s20, 31
	s_lshl_b64 s[22:23], s[20:21], 19
	s_add_u32 s22, s56, s22
	s_addc_u32 s23, s57, s23
	s_and_b64 s[50:51], s[8:9], exec
	s_cselect_b32 s21, s23, s67
	s_cselect_b32 s74, s22, s66
	s_ashr_i32 s15, s14, 31
	s_lshl_b64 s[50:51], s[14:15], 19
	s_add_u32 s60, s5, s50
	s_addc_u32 s61, s6, s51
	s_and_b64 s[50:51], s[8:9], exec
	s_cselect_b32 s15, s61, s65
	s_cselect_b32 s75, s60, s64
	s_add_u32 s76, s64, 0x100
	s_addc_u32 s77, s65, 0
	s_add_u32 s64, s66, 0x40080
	s_addc_u32 s65, s67, 0
	s_mov_b32 s78, -2
	s_add_u32 s50, s64, 0xfffc0080
	s_addc_u32 s51, s65, -1
	s_add_i32 s79, 0, 0x10000
	s_cmp_eq_u32 s78, 12
	s_cselect_b32 s69, s21, s51
	s_cselect_b32 s68, s74, s50
	s_cselect_b32 s67, s15, s77
	s_cselect_b32 s66, s75, s76
	s_add_u32 s98, s66, 0x80
	s_addc_u32 s99, s67, 0
	s_add_u32 s100, s68, 0x80
	s_addc_u32 s101, s69, 0
	s_add_i32 s80, 0, 0x14000
	v_add_u32_e32 v156, s79, v143
	v_add_u32_e32 v160, s80, v143
	ds_read_b128 v[138:141], v156
	ds_read_b128 v[148:151], v156 offset:1024
	ds_read_b128 v[152:155], v156 offset:2048
	ds_read_b128 v[156:159], v156 offset:3072
	ds_read_b128 v[188:191], v160
	ds_read_b128 v[192:195], v160 offset:1024
	ds_read_b128 v[196:199], v160 offset:2048
	ds_read_b128 v[200:203], v160 offset:3072
	ds_read_b128 v[204:207], v147
	ds_read_b128 v[208:211], v147 offset:1024
	ds_read_b128 v[212:215], v147 offset:2048
	ds_read_b128 v[216:219], v147 offset:3072
	ds_read_b128 v[220:223], v147 offset:4096
	ds_read_b128 v[224:227], v147 offset:5120
	ds_read_b128 v[228:231], v147 offset:6144
	ds_read_b128 v[232:235], v147 offset:7168
	s_add_i32 m0, s7, 0x1c000
	s_nop 0
	global_load_lds_dwordx4 v144, s[82:83]
	s_add_i32 m0, s7, 0x1e000
	s_nop 0
	global_load_lds_dwordx4 v128, s[82:83]
	s_add_i32 m0, s19, 0xc000
	s_nop 0
	global_load_lds_dwordx4 v136, s[64:65]
	s_add_i32 m0, s19, 0xe000
	s_nop 0
	global_load_lds_dwordx4 v134, s[64:65]
	s_waitcnt vmcnt(8)
	s_waitcnt lgkmcnt(0)
	s_barrier
	s_setprio 1
	s_waitcnt lgkmcnt(0)
	v_mfma_f32_16x16x32_bf16 v[124:127], v[138:141], v[204:207], 0
	v_mfma_f32_16x16x32_bf16 v[116:119], v[152:155], v[204:207], 0
	v_mfma_f32_16x16x32_bf16 v[108:111], v[138:141], v[212:215], 0
	v_mfma_f32_16x16x32_bf16 v[100:103], v[152:155], v[212:215], 0
	v_mfma_f32_16x16x32_bf16 v[92:95], v[138:141], v[220:223], 0
	v_mfma_f32_16x16x32_bf16 v[84:87], v[152:155], v[220:223], 0
	v_mfma_f32_16x16x32_bf16 v[76:79], v[138:141], v[228:231], 0
	v_mfma_f32_16x16x32_bf16 v[68:71], v[152:155], v[228:231], 0
	v_mfma_f32_16x16x32_bf16 v[124:127], v[148:151], v[208:211], v[124:127]
	v_mfma_f32_16x16x32_bf16 v[116:119], v[156:159], v[208:211], v[116:119]
	v_mfma_f32_16x16x32_bf16 v[108:111], v[148:151], v[216:219], v[108:111]
	v_mfma_f32_16x16x32_bf16 v[100:103], v[156:159], v[216:219], v[100:103]
	v_mfma_f32_16x16x32_bf16 v[92:95], v[148:151], v[224:227], v[92:95]
	v_mfma_f32_16x16x32_bf16 v[84:87], v[156:159], v[224:227], v[84:87]
	v_mfma_f32_16x16x32_bf16 v[76:79], v[148:151], v[232:235], v[76:79]
	v_mfma_f32_16x16x32_bf16 v[68:71], v[156:159], v[232:235], v[68:71]
	s_setprio 0
	s_setprio 1
	v_mfma_f32_16x16x32_bf16 v[120:123], v[188:191], v[204:207], 0
	v_mfma_f32_16x16x32_bf16 v[112:115], v[196:199], v[204:207], 0
	v_mfma_f32_16x16x32_bf16 v[104:107], v[188:191], v[212:215], 0
	v_mfma_f32_16x16x32_bf16 v[96:99], v[196:199], v[212:215], 0
	v_mfma_f32_16x16x32_bf16 v[88:91], v[188:191], v[220:223], 0
	v_mfma_f32_16x16x32_bf16 v[80:83], v[196:199], v[220:223], 0
	v_mfma_f32_16x16x32_bf16 v[72:75], v[188:191], v[228:231], 0
	v_mfma_f32_16x16x32_bf16 v[64:67], v[196:199], v[228:231], 0
	v_mfma_f32_16x16x32_bf16 v[120:123], v[192:195], v[208:211], v[120:123]
	v_mfma_f32_16x16x32_bf16 v[112:115], v[200:203], v[208:211], v[112:115]
	v_mfma_f32_16x16x32_bf16 v[104:107], v[192:195], v[216:219], v[104:107]
	v_mfma_f32_16x16x32_bf16 v[96:99], v[200:203], v[216:219], v[96:99]
	v_mfma_f32_16x16x32_bf16 v[88:91], v[192:195], v[224:227], v[88:91]
	v_mfma_f32_16x16x32_bf16 v[80:83], v[200:203], v[224:227], v[80:83]
	v_mfma_f32_16x16x32_bf16 v[72:75], v[192:195], v[232:235], v[72:75]
	v_mfma_f32_16x16x32_bf16 v[64:67], v[200:203], v[232:235], v[64:67]
	s_setprio 0
	s_barrier
	s_add_i32 s50, s79, s7
	s_mov_b32 m0, s50
	ds_read_b128 v[204:207], v147 offset:16384
	ds_read_b128 v[208:211], v147 offset:17408
	ds_read_b128 v[212:215], v147 offset:18432
	ds_read_b128 v[216:219], v147 offset:19456
	ds_read_b128 v[220:223], v147 offset:20480
	ds_read_b128 v[224:227], v147 offset:21504
	ds_read_b128 v[228:231], v147 offset:22528
	ds_read_b128 v[232:235], v147 offset:23552
	global_load_lds_dwordx4 v144, s[66:67]
	s_add_i32 m0, s50, 0x2000
	s_add_u32 s50, s66, 0x40000
	s_addc_u32 s51, s67, 0
	s_add_i32 s79, s80, s7
	global_load_lds_dwordx4 v128, s[66:67]
	s_mov_b32 m0, s19
	s_nop 0
	global_load_lds_dwordx4 v132, s[68:69]
	s_mov_b32 m0, s24
	s_nop 0
	global_load_lds_dwordx4 v130, s[68:69]
	s_waitcnt vmcnt(6)
	s_waitcnt lgkmcnt(0)
	s_barrier
; #define PG8_STAGE(bufoff, gbase, voff) do { _Pragma("unroll") for (int _i = 0; _i < 2; ++_i) \
;         __builtin_amdgcn_global_load_lds((const unsigned*)((const char*)(gbase) + (voff)[_i]), (PG8_LAS unsigned*)(lds + (bufoff) + ldsw + _i * 8192), 16, 0, 0); } while (0)
; #define PG8_LDA(dst, b, h) do { _Pragma("unroll") for (int m = 0; m < 4; ++m) _Pragma("unroll") for (int k = 0; k < 2; ++k) dst[m][k] = *(const PG8_LAS bf16x8*)(lds + PG8_SA(b, h) + aoff + m * 2048 + k * 1024); } while (0)
; #define PG8_LDB(dst, b, h) do { _Pragma("unroll") for (int n = 0; n < 2; ++n) _Pragma("unroll") for (int k = 0; k < 2; ++k) dst[n][k] = *(const PG8_LAS bf16x8*)(lds + PG8_SB(b, h) + boff + n * 2048 + k * 1024); } while (0)
; #define PG8_MMA(ai, bj, At, Bt) do { __builtin_amdgcn_s_setprio(1); _Pragma("unroll") for (int m = 0; m < 4; ++m) _Pragma("unroll") for (int n = 0; n < 2; ++n) _Pragma("unroll") for (int k = 0; k < 2; ++k) \
;         acc[ai][bj][m][n] = __builtin_amdgcn_mfma_f32_16x16x32_bf16(Bt[n][k], At[m][k], acc[ai][bj][m][n], 0, 0, 0); __builtin_amdgcn_s_setprio(0); } while (0)
; #define PG8_WAIT_V(n) asm volatile("s_waitcnt vmcnt(" #n ")" ::: "memory")
; #define PG8_WAIT_L(n) asm volatile("s_waitcnt lgkmcnt(" #n ")" ::: "memory")
; #define PG8_BAR __builtin_amdgcn_s_barrier()
; #define PG8_SCHED __builtin_amdgcn_sched_barrier(0)
; template <class Epi, class Sched, bool ALIGN_EPI = false, bool SP2 = false>
; __device__ __forceinline__ void gemm_phase(PG8_LAS unsigned char* lds, const Gemm g, const Sched& S, const Epi& E) {
;     ...
;             PG8_WAIT_V(8); PG8_WAIT_L(0); PG8_BAR; PG8_MMA(1, 0, At, B0); PG8_MMA(1, 1, At, B1); PG8_BAR; PG8_SCHED;
;             PG8_LDB(B0, 1, 0); PG8_LDB(B1, 1, 1); PG8_SCHED; PG8_LDA(At, 1, 0); PG8_STAGE(PG8_SA(0, 1), a2 + hstepA, voffA);
;             PG8_WAIT_V(8); PG8_WAIT_L(0); PG8_BAR; PG8_MMA(0, 0, At, B0); PG8_MMA(0, 1, At, B1); PG8_BAR; PG8_SCHED;
	s_setprio 1
	s_waitcnt lgkmcnt(0)
	v_mfma_f32_16x16x32_bf16 v[60:63], v[138:141], v[204:207], 0
	v_mfma_f32_16x16x32_bf16 v[52:55], v[152:155], v[204:207], 0
	v_mfma_f32_16x16x32_bf16 v[44:47], v[138:141], v[212:215], 0
	v_mfma_f32_16x16x32_bf16 v[36:39], v[152:155], v[212:215], 0
	v_mfma_f32_16x16x32_bf16 v[28:31], v[138:141], v[220:223], 0
	v_mfma_f32_16x16x32_bf16 v[20:23], v[152:155], v[220:223], 0
	v_mfma_f32_16x16x32_bf16 v[12:15], v[138:141], v[228:231], 0
	v_mfma_f32_16x16x32_bf16 v[4:7], v[152:155], v[228:231], 0
	v_mfma_f32_16x16x32_bf16 v[60:63], v[148:151], v[208:211], v[60:63]
	v_mfma_f32_16x16x32_bf16 v[52:55], v[156:159], v[208:211], v[52:55]
	v_mfma_f32_16x16x32_bf16 v[44:47], v[148:151], v[216:219], v[44:47]
	v_mfma_f32_16x16x32_bf16 v[36:39], v[156:159], v[216:219], v[36:39]
	v_mfma_f32_16x16x32_bf16 v[28:31], v[148:151], v[224:227], v[28:31]
	v_mfma_f32_16x16x32_bf16 v[20:23], v[156:159], v[224:227], v[20:23]
	v_mfma_f32_16x16x32_bf16 v[12:15], v[148:151], v[232:235], v[12:15]
	v_mfma_f32_16x16x32_bf16 v[4:7], v[156:159], v[232:235], v[4:7]
	s_setprio 0
	s_setprio 1
	v_mfma_f32_16x16x32_bf16 v[56:59], v[188:191], v[204:207], 0
	v_mfma_f32_16x16x32_bf16 v[48:51], v[196:199], v[204:207], 0
	v_mfma_f32_16x16x32_bf16 v[40:43], v[188:191], v[212:215], 0
	v_mfma_f32_16x16x32_bf16 v[32:35], v[196:199], v[212:215], 0
	v_mfma_f32_16x16x32_bf16 v[24:27], v[188:191], v[220:223], 0
	v_mfma_f32_16x16x32_bf16 v[16:19], v[196:199], v[220:223], 0
	v_mfma_f32_16x16x32_bf16 v[8:11], v[188:191], v[228:231], 0
	v_mfma_f32_16x16x32_bf16 v[0:3], v[196:199], v[228:231], 0
	v_mfma_f32_16x16x32_bf16 v[56:59], v[192:195], v[208:211], v[56:59]
	v_mfma_f32_16x16x32_bf16 v[48:51], v[200:203], v[208:211], v[48:51]
	v_mfma_f32_16x16x32_bf16 v[40:43], v[192:195], v[216:219], v[40:43]
	v_mfma_f32_16x16x32_bf16 v[32:35], v[200:203], v[216:219], v[32:35]
	v_mfma_f32_16x16x32_bf16 v[24:27], v[192:195], v[224:227], v[24:27]
	v_mfma_f32_16x16x32_bf16 v[16:19], v[200:203], v[224:227], v[16:19]
	v_mfma_f32_16x16x32_bf16 v[8:11], v[192:195], v[232:235], v[8:11]
	v_mfma_f32_16x16x32_bf16 v[0:3], v[200:203], v[232:235], v[0:3]
	s_setprio 0
	s_barrier
	s_add_i32 s79, 0, 0x18000
	s_add_i32 s80, 0, 0x1c000
	v_add_u32_e32 v156, s79, v143
	v_add_u32_e32 v162, s80, v143
	ds_read_b128 v[138:141], v156
	ds_read_b128 v[148:151], v156 offset:1024
	ds_read_b128 v[152:155], v156 offset:2048
	ds_read_b128 v[156:159], v156 offset:3072
	ds_read_b128 v[188:191], v162
	ds_read_b128 v[192:195], v162 offset:1024
	ds_read_b128 v[196:199], v162 offset:2048
	ds_read_b128 v[200:203], v162 offset:3072
	s_add_u32 s50, s68, 0x40000
	s_addc_u32 s51, s69, 0
	ds_read_b128 v[204:207], v147 offset:32768
	ds_read_b128 v[208:211], v147 offset:33792
	ds_read_b128 v[212:215], v147 offset:34816
	ds_read_b128 v[216:219], v147 offset:35840
	ds_read_b128 v[220:223], v147 offset:36864
	ds_read_b128 v[224:227], v147 offset:37888
	ds_read_b128 v[228:231], v147 offset:38912
	ds_read_b128 v[232:235], v147 offset:39936
	s_add_u32 s84, s66, 0x40000
	s_addc_u32 s85, s67, 0
	s_add_i32 m0, s7, 0x14000
	s_nop 0
	global_load_lds_dwordx4 v144, s[84:85]
	s_add_i32 m0, s7, 0x16000
	s_nop 0
	global_load_lds_dwordx4 v128, s[84:85]
	s_mov_b32 m0, s25
	s_nop 0
	global_load_lds_dwordx4 v132, s[50:51]
	s_mov_b32 m0, s31
	s_nop 0
	global_load_lds_dwordx4 v130, s[50:51]
	s_waitcnt vmcnt(8)
	s_waitcnt lgkmcnt(0)
	s_barrier
	s_setprio 1
	s_waitcnt lgkmcnt(0)
	v_mfma_f32_16x16x32_bf16 v[124:127], v[138:141], v[204:207], v[124:127]
	v_mfma_f32_16x16x32_bf16 v[116:119], v[152:155], v[204:207], v[116:119]
	v_mfma_f32_16x16x32_bf16 v[108:111], v[138:141], v[212:215], v[108:111]
	v_mfma_f32_16x16x32_bf16 v[100:103], v[152:155], v[212:215], v[100:103]
	v_mfma_f32_16x16x32_bf16 v[92:95], v[138:141], v[220:223], v[92:95]
	v_mfma_f32_16x16x32_bf16 v[84:87], v[152:155], v[220:223], v[84:87]
	v_mfma_f32_16x16x32_bf16 v[76:79], v[138:141], v[228:231], v[76:79]
	v_mfma_f32_16x16x32_bf16 v[68:71], v[152:155], v[228:231], v[68:71]
	v_mfma_f32_16x16x32_bf16 v[124:127], v[148:151], v[208:211], v[124:127]
	v_mfma_f32_16x16x32_bf16 v[116:119], v[156:159], v[208:211], v[116:119]
	v_mfma_f32_16x16x32_bf16 v[108:111], v[148:151], v[216:219], v[108:111]
	v_mfma_f32_16x16x32_bf16 v[100:103], v[156:159], v[216:219], v[100:103]
	v_mfma_f32_16x16x32_bf16 v[92:95], v[148:151], v[224:227], v[92:95]
	v_mfma_f32_16x16x32_bf16 v[84:87], v[156:159], v[224:227], v[84:87]
	v_mfma_f32_16x16x32_bf16 v[76:79], v[148:151], v[232:235], v[76:79]
	v_mfma_f32_16x16x32_bf16 v[68:71], v[156:159], v[232:235], v[68:71]
	s_setprio 0
	s_setprio 1
	v_mfma_f32_16x16x32_bf16 v[120:123], v[188:191], v[204:207], v[120:123]
	v_mfma_f32_16x16x32_bf16 v[112:115], v[196:199], v[204:207], v[112:115]
	v_mfma_f32_16x16x32_bf16 v[104:107], v[188:191], v[212:215], v[104:107]
	v_mfma_f32_16x16x32_bf16 v[96:99], v[196:199], v[212:215], v[96:99]
	v_mfma_f32_16x16x32_bf16 v[88:91], v[188:191], v[220:223], v[88:91]
	v_mfma_f32_16x16x32_bf16 v[80:83], v[196:199], v[220:223], v[80:83]
	v_mfma_f32_16x16x32_bf16 v[72:75], v[188:191], v[228:231], v[72:75]
	v_mfma_f32_16x16x32_bf16 v[64:67], v[196:199], v[228:231], v[64:67]
	v_mfma_f32_16x16x32_bf16 v[120:123], v[192:195], v[208:211], v[120:123]
	v_mfma_f32_16x16x32_bf16 v[112:115], v[200:203], v[208:211], v[112:115]
	v_mfma_f32_16x16x32_bf16 v[104:107], v[192:195], v[216:219], v[104:107]
	v_mfma_f32_16x16x32_bf16 v[96:99], v[200:203], v[216:219], v[96:99]
	v_mfma_f32_16x16x32_bf16 v[88:91], v[192:195], v[224:227], v[88:91]
	v_mfma_f32_16x16x32_bf16 v[80:83], v[200:203], v[224:227], v[80:83]
	v_mfma_f32_16x16x32_bf16 v[72:75], v[192:195], v[232:235], v[72:75]
	v_mfma_f32_16x16x32_bf16 v[64:67], v[200:203], v[232:235], v[64:67]
	s_setprio 0
	s_barrier
; #define PG8_STAGE(bufoff, gbase, voff) do { _Pragma("unroll") for (int _i = 0; _i < 2; ++_i) \
;         __builtin_amdgcn_global_load_lds((const unsigned*)((const char*)(gbase) + (voff)[_i]), (PG8_LAS unsigned*)(lds + (bufoff) + ldsw + _i * 8192), 16, 0, 0); } while (0)
; #define PG8_LDA(dst, b, h) do { _Pragma("unroll") for (int m = 0; m < 4; ++m) _Pragma("unroll") for (int k = 0; k < 2; ++k) dst[m][k] = *(const PG8_LAS bf16x8*)(lds + PG8_SA(b, h) + aoff + m * 2048 + k * 1024); } while (0)
; #define PG8_LDB(dst, b, h) do { _Pragma("unroll") for (int n = 0; n < 2; ++n) _Pragma("unroll") for (int k = 0; k < 2; ++k) dst[n][k] = *(const PG8_LAS bf16x8*)(lds + PG8_SB(b, h) + boff + n * 2048 + k * 1024); } while (0)
; #define PG8_MMA(ai, bj, At, Bt) do { __builtin_amdgcn_s_setprio(1); _Pragma("unroll") for (int m = 0; m < 4; ++m) _Pragma("unroll") for (int n = 0; n < 2; ++n) _Pragma("unroll") for (int k = 0; k < 2; ++k) \
;         acc[ai][bj][m][n] = __builtin_amdgcn_mfma_f32_16x16x32_bf16(Bt[n][k], At[m][k], acc[ai][bj][m][n], 0, 0, 0); __builtin_amdgcn_s_setprio(0); } while (0)
; #define PG8_WAIT_V(n) asm volatile("s_waitcnt vmcnt(" #n ")" ::: "memory")
; #define PG8_WAIT_L(n) asm volatile("s_waitcnt lgkmcnt(" #n ")" ::: "memory")
; #define PG8_BAR __builtin_amdgcn_s_barrier()
; #define PG8_SCHED __builtin_amdgcn_sched_barrier(0)
; template <class Epi, class Sched, bool ALIGN_EPI = false, bool SP2 = false>
; __device__ __forceinline__ void gemm_phase(PG8_LAS unsigned char* lds, const Gemm g, const Sched& S, const Epi& E) {
;     ...
;         for (int t = 0; t < nt; t += 2) {
;             const bool last = (t == nt - 2);
;             const char* a1 = cA + (size_t)(t + 1) * kstep;
;             const char* a2 = last ? nA : cA + (size_t)(t + 2) * kstep; const char* b2 = last ? nB : cB + (size_t)(t + 2) * kstep;
;             const char* a3 = a2 + kstep; const char* b3 = b2 + kstep;
;             if (last && has_next) S.a_ready(nxt);
;             if constexpr (SP2) {
;             PG8_LDB(B0, 0, 0); PG8_LDB(B1, 0, 1); PG8_SCHED; PG8_LDA(At, 0, 0); PG8_STAGE(PG8_SA(1, 1), a1 + hstepA, voffA);
;     ...
;             PG8_LDA(At, 1, 1); PG8_STAGE(PG8_SB(1, 0), b3, voffB); PG8_STAGE(PG8_SB(1, 1), b3 + hstepB, voffB); PG8_STAGE(PG8_SA(1, 0), a3, voffA);
;             PG8_WAIT_V(8); PG8_WAIT_L(0); PG8_BAR; PG8_MMA(1, 0, At, B0); PG8_MMA(1, 1, At, B1); PG8_BAR; PG8_SCHED;
	s_add_i32 s50, s79, s7
	s_mov_b32 m0, s50
	ds_read_b128 v[204:207], v147 offset:49152
	ds_read_b128 v[208:211], v147 offset:50176
	ds_read_b128 v[212:215], v147 offset:51200
	ds_read_b128 v[216:219], v147 offset:52224
	ds_read_b128 v[220:223], v147 offset:53248
	ds_read_b128 v[224:227], v147 offset:54272
	ds_read_b128 v[228:231], v147 offset:55296
	ds_read_b128 v[232:235], v147 offset:56320
	global_load_lds_dwordx4 v144, s[98:99]
	s_add_i32 m0, s50, 0x2000
	s_add_u32 s82, s66, 0x40080
	s_addc_u32 s83, s67, 0
	global_load_lds_dwordx4 v128, s[98:99]
	s_mov_b32 m0, s70
	s_nop 0
	global_load_lds_dwordx4 v132, s[100:101]
	s_mov_b32 m0, s71
	s_nop 0
	global_load_lds_dwordx4 v130, s[100:101]
	s_waitcnt vmcnt(6)
	s_waitcnt lgkmcnt(0)
	s_barrier
	s_setprio 1
	s_waitcnt lgkmcnt(0)
	v_mfma_f32_16x16x32_bf16 v[60:63], v[138:141], v[204:207], v[60:63]
	v_mfma_f32_16x16x32_bf16 v[52:55], v[152:155], v[204:207], v[52:55]
	v_mfma_f32_16x16x32_bf16 v[44:47], v[138:141], v[212:215], v[44:47]
	v_mfma_f32_16x16x32_bf16 v[36:39], v[152:155], v[212:215], v[36:39]
	v_mfma_f32_16x16x32_bf16 v[28:31], v[138:141], v[220:223], v[28:31]
	v_mfma_f32_16x16x32_bf16 v[20:23], v[152:155], v[220:223], v[20:23]
	v_mfma_f32_16x16x32_bf16 v[12:15], v[138:141], v[228:231], v[12:15]
	v_mfma_f32_16x16x32_bf16 v[4:7], v[152:155], v[228:231], v[4:7]
	v_mfma_f32_16x16x32_bf16 v[60:63], v[148:151], v[208:211], v[60:63]
	v_mfma_f32_16x16x32_bf16 v[52:55], v[156:159], v[208:211], v[52:55]
	v_mfma_f32_16x16x32_bf16 v[44:47], v[148:151], v[216:219], v[44:47]
	v_mfma_f32_16x16x32_bf16 v[36:39], v[156:159], v[216:219], v[36:39]
	v_mfma_f32_16x16x32_bf16 v[28:31], v[148:151], v[224:227], v[28:31]
	v_mfma_f32_16x16x32_bf16 v[20:23], v[156:159], v[224:227], v[20:23]
	v_mfma_f32_16x16x32_bf16 v[12:15], v[148:151], v[232:235], v[12:15]
	v_mfma_f32_16x16x32_bf16 v[4:7], v[156:159], v[232:235], v[4:7]
	s_setprio 0
	s_setprio 1
	v_mfma_f32_16x16x32_bf16 v[56:59], v[188:191], v[204:207], v[56:59]
	v_mfma_f32_16x16x32_bf16 v[48:51], v[196:199], v[204:207], v[48:51]
	v_mfma_f32_16x16x32_bf16 v[40:43], v[188:191], v[212:215], v[40:43]
	v_mfma_f32_16x16x32_bf16 v[32:35], v[196:199], v[212:215], v[32:35]
	v_mfma_f32_16x16x32_bf16 v[24:27], v[188:191], v[220:223], v[24:27]
	v_mfma_f32_16x16x32_bf16 v[16:19], v[196:199], v[220:223], v[16:19]
	v_mfma_f32_16x16x32_bf16 v[8:11], v[188:191], v[228:231], v[8:11]
	v_mfma_f32_16x16x32_bf16 v[0:3], v[196:199], v[228:231], v[0:3]
	v_mfma_f32_16x16x32_bf16 v[56:59], v[192:195], v[208:211], v[56:59]
	v_mfma_f32_16x16x32_bf16 v[48:51], v[200:203], v[208:211], v[48:51]
	v_mfma_f32_16x16x32_bf16 v[40:43], v[192:195], v[216:219], v[40:43]
	v_mfma_f32_16x16x32_bf16 v[32:35], v[200:203], v[216:219], v[32:35]
	v_mfma_f32_16x16x32_bf16 v[24:27], v[192:195], v[224:227], v[24:27]
	v_mfma_f32_16x16x32_bf16 v[16:19], v[200:203], v[224:227], v[16:19]
	v_mfma_f32_16x16x32_bf16 v[8:11], v[192:195], v[232:235], v[8:11]
	v_mfma_f32_16x16x32_bf16 v[0:3], v[200:203], v[232:235], v[0:3]
	s_setprio 0
	s_barrier
	s_add_i32 s78, s78, 2
	s_add_u32 s76, s76, 0x100
	s_addc_u32 s77, s77, 0
	s_add_u32 s64, s64, 0x100
	s_addc_u32 s65, s65, 0
.LBB0_444:
	s_add_u32 s50, s64, 0xfffc0080
	s_addc_u32 s51, s65, -1
	s_add_i32 s79, 0, 0x10000
	s_cmp_eq_u32 s78, 12
	s_cselect_b32 s69, s21, s51
	s_cselect_b32 s68, s74, s50
	s_cselect_b32 s67, s15, s77
	s_cselect_b32 s66, s75, s76
	s_add_u32 s98, s66, 0x80
	s_addc_u32 s99, s67, 0
	s_add_u32 s100, s68, 0x80
	s_addc_u32 s101, s69, 0
	s_add_i32 s80, 0, 0x14000
	v_add_u32_e32 v156, s79, v143
	v_add_u32_e32 v160, s80, v143
	ds_read_b128 v[138:141], v156
	ds_read_b128 v[148:151], v156 offset:1024
	ds_read_b128 v[152:155], v156 offset:2048
	ds_read_b128 v[156:159], v156 offset:3072
	ds_read_b128 v[188:191], v160
	ds_read_b128 v[192:195], v160 offset:1024
	ds_read_b128 v[196:199], v160 offset:2048
	ds_read_b128 v[200:203], v160 offset:3072
	ds_read_b128 v[204:207], v147
	ds_read_b128 v[208:211], v147 offset:1024
	ds_read_b128 v[212:215], v147 offset:2048
	ds_read_b128 v[216:219], v147 offset:3072
	ds_read_b128 v[220:223], v147 offset:4096
	ds_read_b128 v[224:227], v147 offset:5120
	ds_read_b128 v[228:231], v147 offset:6144
	ds_read_b128 v[232:235], v147 offset:7168
	s_add_i32 m0, s7, 0x1c000
	s_nop 0
	global_load_lds_dwordx4 v144, s[82:83]
	s_add_i32 m0, s7, 0x1e000
	s_nop 0
	global_load_lds_dwordx4 v128, s[82:83]
	s_add_i32 m0, s19, 0xc000
	s_nop 0
	global_load_lds_dwordx4 v136, s[64:65]
	s_add_i32 m0, s19, 0xe000
	s_nop 0
	global_load_lds_dwordx4 v134, s[64:65]
	s_waitcnt vmcnt(8)
	s_waitcnt lgkmcnt(0)
	s_barrier
; #define PG8_STAGE(bufoff, gbase, voff) do { _Pragma("unroll") for (int _i = 0; _i < 2; ++_i) \
;         __builtin_amdgcn_global_load_lds((const unsigned*)((const char*)(gbase) + (voff)[_i]), (PG8_LAS unsigned*)(lds + (bufoff) + ldsw + _i * 8192), 16, 0, 0); } while (0)
; #define PG8_LDA(dst, b, h) do { _Pragma("unroll") for (int m = 0; m < 4; ++m) _Pragma("unroll") for (int k = 0; k < 2; ++k) dst[m][k] = *(const PG8_LAS bf16x8*)(lds + PG8_SA(b, h) + aoff + m * 2048 + k * 1024); } while (0)
; #define PG8_MMA(ai, bj, At, Bt) do { __builtin_amdgcn_s_setprio(1); _Pragma("unroll") for (int m = 0; m < 4; ++m) _Pragma("unroll") for (int n = 0; n < 2; ++n) _Pragma("unroll") for (int k = 0; k < 2; ++k) \
;         acc[ai][bj][m][n] = __builtin_amdgcn_mfma_f32_16x16x32_bf16(Bt[n][k], At[m][k], acc[ai][bj][m][n], 0, 0, 0); __builtin_amdgcn_s_setprio(0); } while (0)
; #define PG8_WAIT_V(n) asm volatile("s_waitcnt vmcnt(" #n ")" ::: "memory")
; #define PG8_WAIT_L(n) asm volatile("s_waitcnt lgkmcnt(" #n ")" ::: "memory")
; #define PG8_BAR __builtin_amdgcn_s_barrier()
; #define PG8_SCHED __builtin_amdgcn_sched_barrier(0)
; template <class Epi, class Sched, bool ALIGN_EPI = false, bool SP2 = false>
; __device__ __forceinline__ void gemm_phase(PG8_LAS unsigned char* lds, const Gemm g, const Sched& S, const Epi& E) {
;     ...
;             PG8_WAIT_V(8); PG8_WAIT_L(0); PG8_BAR; PG8_MMA(0, 0, At, B0); PG8_MMA(0, 1, At, B1); PG8_BAR; PG8_SCHED;
;             PG8_LDA(At, 0, 1); PG8_STAGE(PG8_SB(0, 0), b2, voffB); PG8_STAGE(PG8_SB(0, 1), b2 + hstepB, voffB); PG8_STAGE(PG8_SA(0, 0), a2, voffA);
;             PG8_WAIT_V(8); PG8_WAIT_L(0); PG8_BAR; PG8_MMA(1, 0, At, B0); PG8_MMA(1, 1, At, B1); PG8_BAR; PG8_SCHED;
	s_setprio 1
	s_waitcnt lgkmcnt(0)
	v_mfma_f32_16x16x32_bf16 v[124:127], v[138:141], v[204:207], v[124:127]
	v_mfma_f32_16x16x32_bf16 v[116:119], v[152:155], v[204:207], v[116:119]
	v_mfma_f32_16x16x32_bf16 v[108:111], v[138:141], v[212:215], v[108:111]
	v_mfma_f32_16x16x32_bf16 v[100:103], v[152:155], v[212:215], v[100:103]
	v_mfma_f32_16x16x32_bf16 v[92:95], v[138:141], v[220:223], v[92:95]
	v_mfma_f32_16x16x32_bf16 v[84:87], v[152:155], v[220:223], v[84:87]
	v_mfma_f32_16x16x32_bf16 v[76:79], v[138:141], v[228:231], v[76:79]
	v_mfma_f32_16x16x32_bf16 v[68:71], v[152:155], v[228:231], v[68:71]
	v_mfma_f32_16x16x32_bf16 v[124:127], v[148:151], v[208:211], v[124:127]
	v_mfma_f32_16x16x32_bf16 v[116:119], v[156:159], v[208:211], v[116:119]
	v_mfma_f32_16x16x32_bf16 v[108:111], v[148:151], v[216:219], v[108:111]
	v_mfma_f32_16x16x32_bf16 v[100:103], v[156:159], v[216:219], v[100:103]
	v_mfma_f32_16x16x32_bf16 v[92:95], v[148:151], v[224:227], v[92:95]
	v_mfma_f32_16x16x32_bf16 v[84:87], v[156:159], v[224:227], v[84:87]
	v_mfma_f32_16x16x32_bf16 v[76:79], v[148:151], v[232:235], v[76:79]
	v_mfma_f32_16x16x32_bf16 v[68:71], v[156:159], v[232:235], v[68:71]
	s_setprio 0
	s_setprio 1
	v_mfma_f32_16x16x32_bf16 v[120:123], v[188:191], v[204:207], v[120:123]
	v_mfma_f32_16x16x32_bf16 v[112:115], v[196:199], v[204:207], v[112:115]
	v_mfma_f32_16x16x32_bf16 v[104:107], v[188:191], v[212:215], v[104:107]
	v_mfma_f32_16x16x32_bf16 v[96:99], v[196:199], v[212:215], v[96:99]
	v_mfma_f32_16x16x32_bf16 v[88:91], v[188:191], v[220:223], v[88:91]
	v_mfma_f32_16x16x32_bf16 v[80:83], v[196:199], v[220:223], v[80:83]
	v_mfma_f32_16x16x32_bf16 v[72:75], v[188:191], v[228:231], v[72:75]
	v_mfma_f32_16x16x32_bf16 v[64:67], v[196:199], v[228:231], v[64:67]
	v_mfma_f32_16x16x32_bf16 v[120:123], v[192:195], v[208:211], v[120:123]
	v_mfma_f32_16x16x32_bf16 v[112:115], v[200:203], v[208:211], v[112:115]
	v_mfma_f32_16x16x32_bf16 v[104:107], v[192:195], v[216:219], v[104:107]
	v_mfma_f32_16x16x32_bf16 v[96:99], v[200:203], v[216:219], v[96:99]
	v_mfma_f32_16x16x32_bf16 v[88:91], v[192:195], v[224:227], v[88:91]
	v_mfma_f32_16x16x32_bf16 v[80:83], v[200:203], v[224:227], v[80:83]
	v_mfma_f32_16x16x32_bf16 v[72:75], v[192:195], v[232:235], v[72:75]
	v_mfma_f32_16x16x32_bf16 v[64:67], v[200:203], v[232:235], v[64:67]
	s_setprio 0
	s_barrier
	s_add_i32 s50, s79, s7
	s_mov_b32 m0, s50
	ds_read_b128 v[204:207], v147 offset:16384
	ds_read_b128 v[208:211], v147 offset:17408
	ds_read_b128 v[212:215], v147 offset:18432
	ds_read_b128 v[216:219], v147 offset:19456
	ds_read_b128 v[220:223], v147 offset:20480
	ds_read_b128 v[224:227], v147 offset:21504
	ds_read_b128 v[228:231], v147 offset:22528
	ds_read_b128 v[232:235], v147 offset:23552
	global_load_lds_dwordx4 v144, s[66:67]
	s_add_i32 m0, s50, 0x2000
	s_add_u32 s50, s66, 0x40000
	s_addc_u32 s51, s67, 0
	s_add_i32 s79, s80, s7
	global_load_lds_dwordx4 v128, s[66:67]
	s_mov_b32 m0, s19
	s_nop 0
	global_load_lds_dwordx4 v132, s[68:69]
	s_mov_b32 m0, s24
	s_nop 0
	global_load_lds_dwordx4 v130, s[68:69]
	s_waitcnt vmcnt(6)
	s_waitcnt lgkmcnt(0)
	s_barrier
	s_setprio 1
	s_waitcnt lgkmcnt(0)
	v_mfma_f32_16x16x32_bf16 v[60:63], v[138:141], v[204:207], v[60:63]
	v_mfma_f32_16x16x32_bf16 v[52:55], v[152:155], v[204:207], v[52:55]
	v_mfma_f32_16x16x32_bf16 v[44:47], v[138:141], v[212:215], v[44:47]
	v_mfma_f32_16x16x32_bf16 v[36:39], v[152:155], v[212:215], v[36:39]
	v_mfma_f32_16x16x32_bf16 v[28:31], v[138:141], v[220:223], v[28:31]
	v_mfma_f32_16x16x32_bf16 v[20:23], v[152:155], v[220:223], v[20:23]
	v_mfma_f32_16x16x32_bf16 v[12:15], v[138:141], v[228:231], v[12:15]
	v_mfma_f32_16x16x32_bf16 v[4:7], v[152:155], v[228:231], v[4:7]
	v_mfma_f32_16x16x32_bf16 v[60:63], v[148:151], v[208:211], v[60:63]
	v_mfma_f32_16x16x32_bf16 v[52:55], v[156:159], v[208:211], v[52:55]
	v_mfma_f32_16x16x32_bf16 v[44:47], v[148:151], v[216:219], v[44:47]
	v_mfma_f32_16x16x32_bf16 v[36:39], v[156:159], v[216:219], v[36:39]
	v_mfma_f32_16x16x32_bf16 v[28:31], v[148:151], v[224:227], v[28:31]
	v_mfma_f32_16x16x32_bf16 v[20:23], v[156:159], v[224:227], v[20:23]
	v_mfma_f32_16x16x32_bf16 v[12:15], v[148:151], v[232:235], v[12:15]
	v_mfma_f32_16x16x32_bf16 v[4:7], v[156:159], v[232:235], v[4:7]
	s_setprio 0
	s_setprio 1
	v_mfma_f32_16x16x32_bf16 v[56:59], v[188:191], v[204:207], v[56:59]
	v_mfma_f32_16x16x32_bf16 v[48:51], v[196:199], v[204:207], v[48:51]
	v_mfma_f32_16x16x32_bf16 v[40:43], v[188:191], v[212:215], v[40:43]
	v_mfma_f32_16x16x32_bf16 v[32:35], v[196:199], v[212:215], v[32:35]
	v_mfma_f32_16x16x32_bf16 v[24:27], v[188:191], v[220:223], v[24:27]
	v_mfma_f32_16x16x32_bf16 v[16:19], v[196:199], v[220:223], v[16:19]
	v_mfma_f32_16x16x32_bf16 v[8:11], v[188:191], v[228:231], v[8:11]
	v_mfma_f32_16x16x32_bf16 v[0:3], v[196:199], v[228:231], v[0:3]
	v_mfma_f32_16x16x32_bf16 v[56:59], v[192:195], v[208:211], v[56:59]
	v_mfma_f32_16x16x32_bf16 v[48:51], v[200:203], v[208:211], v[48:51]
	v_mfma_f32_16x16x32_bf16 v[40:43], v[192:195], v[216:219], v[40:43]
	v_mfma_f32_16x16x32_bf16 v[32:35], v[200:203], v[216:219], v[32:35]
	v_mfma_f32_16x16x32_bf16 v[24:27], v[192:195], v[224:227], v[24:27]
	v_mfma_f32_16x16x32_bf16 v[16:19], v[200:203], v[224:227], v[16:19]
	v_mfma_f32_16x16x32_bf16 v[8:11], v[192:195], v[232:235], v[8:11]
	v_mfma_f32_16x16x32_bf16 v[0:3], v[200:203], v[232:235], v[0:3]
	s_setprio 0
	s_barrier
; #define PG8_STAGE(bufoff, gbase, voff) do { _Pragma("unroll") for (int _i = 0; _i < 2; ++_i) \
;         __builtin_amdgcn_global_load_lds((const unsigned*)((const char*)(gbase) + (voff)[_i]), (PG8_LAS unsigned*)(lds + (bufoff) + ldsw + _i * 8192), 16, 0, 0); } while (0)
; #define PG8_LDA(dst, b, h) do { _Pragma("unroll") for (int m = 0; m < 4; ++m) _Pragma("unroll") for (int k = 0; k < 2; ++k) dst[m][k] = *(const PG8_LAS bf16x8*)(lds + PG8_SA(b, h) + aoff + m * 2048 + k * 1024); } while (0)
; #define PG8_LDB(dst, b, h) do { _Pragma("unroll") for (int n = 0; n < 2; ++n) _Pragma("unroll") for (int k = 0; k < 2; ++k) dst[n][k] = *(const PG8_LAS bf16x8*)(lds + PG8_SB(b, h) + boff + n * 2048 + k * 1024); } while (0)
; #define PG8_MMA(ai, bj, At, Bt) do { __builtin_amdgcn_s_setprio(1); _Pragma("unroll") for (int m = 0; m < 4; ++m) _Pragma("unroll") for (int n = 0; n < 2; ++n) _Pragma("unroll") for (int k = 0; k < 2; ++k) \
;         acc[ai][bj][m][n] = __builtin_amdgcn_mfma_f32_16x16x32_bf16(Bt[n][k], At[m][k], acc[ai][bj][m][n], 0, 0, 0); __builtin_amdgcn_s_setprio(0); } while (0)
; #define PG8_WAIT_V(n) asm volatile("s_waitcnt vmcnt(" #n ")" ::: "memory")
; #define PG8_WAIT_L(n) asm volatile("s_waitcnt lgkmcnt(" #n ")" ::: "memory")
; #define PG8_BAR __builtin_amdgcn_s_barrier()
; #define PG8_SCHED __builtin_amdgcn_sched_barrier(0)
; template <class Epi, class Sched, bool ALIGN_EPI = false, bool SP2 = false>
; __device__ __forceinline__ void gemm_phase(PG8_LAS unsigned char* lds, const Gemm g, const Sched& S, const Epi& E) {
;     ...
;             PG8_LDB(B0, 1, 0); PG8_LDB(B1, 1, 1); PG8_SCHED; PG8_LDA(At, 1, 0); PG8_STAGE(PG8_SA(0, 1), a2 + hstepA, voffA);
;             PG8_WAIT_V(8); PG8_WAIT_L(0); PG8_BAR; PG8_MMA(0, 0, At, B0); PG8_MMA(0, 1, At, B1); PG8_BAR; PG8_SCHED;
;             PG8_LDA(At, 1, 1); PG8_STAGE(PG8_SB(1, 0), b3, voffB); PG8_STAGE(PG8_SB(1, 1), b3 + hstepB, voffB); PG8_STAGE(PG8_SA(1, 0), a3, voffA);
;             PG8_WAIT_V(8); PG8_WAIT_L(0); PG8_BAR; PG8_MMA(1, 0, At, B0); PG8_MMA(1, 1, At, B1); PG8_BAR; PG8_SCHED;
	s_add_i32 s79, 0, 0x18000
	s_add_i32 s80, 0, 0x1c000
	v_add_u32_e32 v156, s79, v143
	v_add_u32_e32 v162, s80, v143
	ds_read_b128 v[138:141], v156
	ds_read_b128 v[148:151], v156 offset:1024
	ds_read_b128 v[152:155], v156 offset:2048
	ds_read_b128 v[156:159], v156 offset:3072
	ds_read_b128 v[188:191], v162
	ds_read_b128 v[192:195], v162 offset:1024
	ds_read_b128 v[196:199], v162 offset:2048
	ds_read_b128 v[200:203], v162 offset:3072
	s_add_u32 s50, s68, 0x40000
	s_addc_u32 s51, s69, 0
	ds_read_b128 v[204:207], v147 offset:32768
	ds_read_b128 v[208:211], v147 offset:33792
	ds_read_b128 v[212:215], v147 offset:34816
	ds_read_b128 v[216:219], v147 offset:35840
	ds_read_b128 v[220:223], v147 offset:36864
	ds_read_b128 v[224:227], v147 offset:37888
	ds_read_b128 v[228:231], v147 offset:38912
	ds_read_b128 v[232:235], v147 offset:39936
	s_add_u32 s84, s66, 0x40000
	s_addc_u32 s85, s67, 0
	s_add_i32 m0, s7, 0x14000
	s_nop 0
	global_load_lds_dwordx4 v144, s[84:85]
	s_add_i32 m0, s7, 0x16000
	s_nop 0
	global_load_lds_dwordx4 v128, s[84:85]
	s_mov_b32 m0, s25
	s_nop 0
	global_load_lds_dwordx4 v132, s[50:51]
	s_mov_b32 m0, s31
	s_nop 0
	global_load_lds_dwordx4 v130, s[50:51]
	s_waitcnt vmcnt(8)
	s_waitcnt lgkmcnt(0)
	s_barrier
	s_setprio 1
	s_waitcnt lgkmcnt(0)
	v_mfma_f32_16x16x32_bf16 v[124:127], v[138:141], v[204:207], v[124:127]
	v_mfma_f32_16x16x32_bf16 v[116:119], v[152:155], v[204:207], v[116:119]
	v_mfma_f32_16x16x32_bf16 v[108:111], v[138:141], v[212:215], v[108:111]
	v_mfma_f32_16x16x32_bf16 v[100:103], v[152:155], v[212:215], v[100:103]
	v_mfma_f32_16x16x32_bf16 v[92:95], v[138:141], v[220:223], v[92:95]
	v_mfma_f32_16x16x32_bf16 v[84:87], v[152:155], v[220:223], v[84:87]
	v_mfma_f32_16x16x32_bf16 v[76:79], v[138:141], v[228:231], v[76:79]
	v_mfma_f32_16x16x32_bf16 v[68:71], v[152:155], v[228:231], v[68:71]
	v_mfma_f32_16x16x32_bf16 v[124:127], v[148:151], v[208:211], v[124:127]
	v_mfma_f32_16x16x32_bf16 v[116:119], v[156:159], v[208:211], v[116:119]
	v_mfma_f32_16x16x32_bf16 v[108:111], v[148:151], v[216:219], v[108:111]
	v_mfma_f32_16x16x32_bf16 v[100:103], v[156:159], v[216:219], v[100:103]
	v_mfma_f32_16x16x32_bf16 v[92:95], v[148:151], v[224:227], v[92:95]
	v_mfma_f32_16x16x32_bf16 v[84:87], v[156:159], v[224:227], v[84:87]
	v_mfma_f32_16x16x32_bf16 v[76:79], v[148:151], v[232:235], v[76:79]
	v_mfma_f32_16x16x32_bf16 v[68:71], v[156:159], v[232:235], v[68:71]
	s_setprio 0
	s_setprio 1
	v_mfma_f32_16x16x32_bf16 v[120:123], v[188:191], v[204:207], v[120:123]
	v_mfma_f32_16x16x32_bf16 v[112:115], v[196:199], v[204:207], v[112:115]
	v_mfma_f32_16x16x32_bf16 v[104:107], v[188:191], v[212:215], v[104:107]
	v_mfma_f32_16x16x32_bf16 v[96:99], v[196:199], v[212:215], v[96:99]
	v_mfma_f32_16x16x32_bf16 v[88:91], v[188:191], v[220:223], v[88:91]
	v_mfma_f32_16x16x32_bf16 v[80:83], v[196:199], v[220:223], v[80:83]
	v_mfma_f32_16x16x32_bf16 v[72:75], v[188:191], v[228:231], v[72:75]
	v_mfma_f32_16x16x32_bf16 v[64:67], v[196:199], v[228:231], v[64:67]
	v_mfma_f32_16x16x32_bf16 v[120:123], v[192:195], v[208:211], v[120:123]
	v_mfma_f32_16x16x32_bf16 v[112:115], v[200:203], v[208:211], v[112:115]
	v_mfma_f32_16x16x32_bf16 v[104:107], v[192:195], v[216:219], v[104:107]
	v_mfma_f32_16x16x32_bf16 v[96:99], v[200:203], v[216:219], v[96:99]
	v_mfma_f32_16x16x32_bf16 v[88:91], v[192:195], v[224:227], v[88:91]
	v_mfma_f32_16x16x32_bf16 v[80:83], v[200:203], v[224:227], v[80:83]
	v_mfma_f32_16x16x32_bf16 v[72:75], v[192:195], v[232:235], v[72:75]
	v_mfma_f32_16x16x32_bf16 v[64:67], v[200:203], v[232:235], v[64:67]
	s_setprio 0
	s_barrier
	s_add_i32 s50, s79, s7
	s_mov_b32 m0, s50
	ds_read_b128 v[204:207], v147 offset:49152
	ds_read_b128 v[208:211], v147 offset:50176
	ds_read_b128 v[212:215], v147 offset:51200
	ds_read_b128 v[216:219], v147 offset:52224
	ds_read_b128 v[220:223], v147 offset:53248
	ds_read_b128 v[224:227], v147 offset:54272
	ds_read_b128 v[228:231], v147 offset:55296
	ds_read_b128 v[232:235], v147 offset:56320
	global_load_lds_dwordx4 v144, s[98:99]
	s_add_i32 m0, s50, 0x2000
	s_add_u32 s82, s66, 0x40080
	s_addc_u32 s83, s67, 0
	global_load_lds_dwordx4 v128, s[98:99]
	s_mov_b32 m0, s70
	s_nop 0
	global_load_lds_dwordx4 v132, s[100:101]
	s_mov_b32 m0, s71
	s_nop 0
	global_load_lds_dwordx4 v130, s[100:101]
	s_waitcnt vmcnt(6)
	s_waitcnt lgkmcnt(0)
	s_barrier
	s_setprio 1
	s_waitcnt lgkmcnt(0)
	v_mfma_f32_16x16x32_bf16 v[60:63], v[138:141], v[204:207], v[60:63]
	v_mfma_f32_16x16x32_bf16 v[52:55], v[152:155], v[204:207], v[52:55]
	v_mfma_f32_16x16x32_bf16 v[44:47], v[138:141], v[212:215], v[44:47]
	v_mfma_f32_16x16x32_bf16 v[36:39], v[152:155], v[212:215], v[36:39]
	v_mfma_f32_16x16x32_bf16 v[28:31], v[138:141], v[220:223], v[28:31]
	v_mfma_f32_16x16x32_bf16 v[20:23], v[152:155], v[220:223], v[20:23]
	v_mfma_f32_16x16x32_bf16 v[12:15], v[138:141], v[228:231], v[12:15]
	v_mfma_f32_16x16x32_bf16 v[4:7], v[152:155], v[228:231], v[4:7]
	v_mfma_f32_16x16x32_bf16 v[60:63], v[148:151], v[208:211], v[60:63]
	v_mfma_f32_16x16x32_bf16 v[52:55], v[156:159], v[208:211], v[52:55]
	v_mfma_f32_16x16x32_bf16 v[44:47], v[148:151], v[216:219], v[44:47]
	v_mfma_f32_16x16x32_bf16 v[36:39], v[156:159], v[216:219], v[36:39]
	v_mfma_f32_16x16x32_bf16 v[28:31], v[148:151], v[224:227], v[28:31]
	v_mfma_f32_16x16x32_bf16 v[20:23], v[156:159], v[224:227], v[20:23]
	v_mfma_f32_16x16x32_bf16 v[12:15], v[148:151], v[232:235], v[12:15]
	v_mfma_f32_16x16x32_bf16 v[4:7], v[156:159], v[232:235], v[4:7]
	s_setprio 0
	s_setprio 1
	v_mfma_f32_16x16x32_bf16 v[56:59], v[188:191], v[204:207], v[56:59]
	v_mfma_f32_16x16x32_bf16 v[48:51], v[196:199], v[204:207], v[48:51]
	v_mfma_f32_16x16x32_bf16 v[40:43], v[188:191], v[212:215], v[40:43]
	v_mfma_f32_16x16x32_bf16 v[32:35], v[196:199], v[212:215], v[32:35]
	v_mfma_f32_16x16x32_bf16 v[24:27], v[188:191], v[220:223], v[24:27]
	v_mfma_f32_16x16x32_bf16 v[16:19], v[196:199], v[220:223], v[16:19]
	v_mfma_f32_16x16x32_bf16 v[8:11], v[188:191], v[228:231], v[8:11]
	v_mfma_f32_16x16x32_bf16 v[0:3], v[196:199], v[228:231], v[0:3]
	v_mfma_f32_16x16x32_bf16 v[56:59], v[192:195], v[208:211], v[56:59]
	v_mfma_f32_16x16x32_bf16 v[48:51], v[200:203], v[208:211], v[48:51]
	v_mfma_f32_16x16x32_bf16 v[40:43], v[192:195], v[216:219], v[40:43]
	v_mfma_f32_16x16x32_bf16 v[32:35], v[200:203], v[216:219], v[32:35]
	v_mfma_f32_16x16x32_bf16 v[24:27], v[192:195], v[224:227], v[24:27]
	v_mfma_f32_16x16x32_bf16 v[16:19], v[200:203], v[224:227], v[16:19]
	v_mfma_f32_16x16x32_bf16 v[8:11], v[192:195], v[232:235], v[8:11]
	v_mfma_f32_16x16x32_bf16 v[0:3], v[200:203], v[232:235], v[0:3]
	s_setprio 0
	s_barrier
	s_add_i32 s78, s78, 2
	s_add_u32 s76, s76, 0x100
	s_addc_u32 s77, s77, 0
	s_add_u32 s64, s64, 0x100
	s_addc_u32 s65, s65, 0
	s_cmp_gt_u32 s78, 13
	s_cbranch_scc0 .LBB0_444
	s_and_b64 vcc, exec, s[12:13]
	s_cbranch_vccz .LBB0_447
	s_barrier
